# s5_pass1 / s5_pass2 weight-fragment loops: fully unrolled with two register sets so the next 16 global loads are in flight while the current 16 MFMAs run
# baseline (speedup 1.0000x reference)
.LBB0_431:
	v_add_co_u32_e32 v50, vcc, 0xffff7000, v16
	s_movk_i32 s10, 0xf000
	s_nop 0
	v_addc_co_u32_e32 v51, vcc, -1, v17, vcc
	v_add_co_u32_e32 v54, vcc, s10, v16
	s_nop 1
	v_addc_co_u32_e32 v55, vcc, -1, v17, vcc
	v_add_co_u32_e32 v82, vcc, s77, v16
	global_load_dwordx4 v[30:33], v[50:51], off offset:-3072
	global_load_dwordx4 v[34:37], v[50:51], off offset:-2048
	global_load_dwordx4 v[38:41], v[54:55], off offset:-3072
	global_load_dwordx4 v[42:45], v[54:55], off offset:-2048
	global_load_dwordx4 v[46:49], v[50:51], off offset:-1024
	s_nop 0
	global_load_dwordx4 v[50:53], v[50:51], off
	v_addc_co_u32_e32 v83, vcc, -1, v17, vcc
	global_load_dwordx4 v[54:57], v[54:55], off offset:-1024
	s_nop 0
	global_load_dwordx4 v[58:61], v[82:83], off offset:-3072
	global_load_dwordx4 v[62:65], v[16:17], off offset:-3072
	global_load_dwordx4 v[66:69], v[16:17], off offset:-2048
	global_load_dwordx4 v[70:73], v[82:83], off offset:-2048
	global_load_dwordx4 v[74:77], v[82:83], off offset:-1024
	global_load_dwordx4 v[78:81], v[16:17], off offset:-4096
	s_nop 0
	global_load_dwordx4 v[82:85], v[82:83], off
	s_nop 0
	global_load_dwordx4 v[86:89], v[16:17], off offset:-1024
	global_load_dwordx4 v[90:93], v[16:17], off
	v_lshl_add_u64 v[16:17], v[16:17], 0, s[12:13]
	v_add_co_u32_e32 v120, vcc, 0xffff7000, v16
	s_movk_i32 s10, 0xf000
	s_nop 0
	v_addc_co_u32_e32 v121, vcc, -1, v17, vcc
	v_add_co_u32_e32 v124, vcc, s10, v16
	s_nop 1
	v_addc_co_u32_e32 v125, vcc, -1, v17, vcc
	v_add_co_u32_e32 v152, vcc, s77, v16
	global_load_dwordx4 v[100:103], v[120:121], off offset:-3072
	global_load_dwordx4 v[104:107], v[120:121], off offset:-2048
	global_load_dwordx4 v[108:111], v[124:125], off offset:-3072
	global_load_dwordx4 v[112:115], v[124:125], off offset:-2048
	global_load_dwordx4 v[116:119], v[120:121], off offset:-1024
	s_nop 0
	global_load_dwordx4 v[120:123], v[120:121], off
	v_addc_co_u32_e32 v153, vcc, -1, v17, vcc
	global_load_dwordx4 v[124:127], v[124:125], off offset:-1024
	s_nop 0
	global_load_dwordx4 v[128:131], v[152:153], off offset:-3072
	global_load_dwordx4 v[132:135], v[16:17], off offset:-3072
	global_load_dwordx4 v[136:139], v[16:17], off offset:-2048
	global_load_dwordx4 v[140:143], v[152:153], off offset:-2048
	global_load_dwordx4 v[144:147], v[152:153], off offset:-1024
	global_load_dwordx4 v[148:151], v[16:17], off offset:-4096
	s_nop 0
	global_load_dwordx4 v[152:155], v[152:153], off
	s_nop 0
	global_load_dwordx4 v[156:159], v[16:17], off offset:-1024
	global_load_dwordx4 v[172:175], v[16:17], off
	v_lshl_add_u64 v[16:17], v[16:17], 0, s[12:13]
	ds_read_b128 v[94:97], v15
	s_waitcnt vmcnt(31) lgkmcnt(0)
	v_mfma_f32_16x16x32_bf16 v[4:7], v[30:33], v[94:97], v[4:7]
	ds_read_b128 v[30:33], v15 offset:64
	s_waitcnt vmcnt(29)
	v_mfma_f32_16x16x32_bf16 v[0:3], v[38:41], v[94:97], v[0:3]
	s_waitcnt lgkmcnt(0)
	v_mfma_f32_16x16x32_bf16 v[4:7], v[34:37], v[30:33], v[4:7]
	s_waitcnt vmcnt(28)
	v_mfma_f32_16x16x32_bf16 v[0:3], v[42:45], v[30:33], v[0:3]
	ds_read_b128 v[30:33], v15 offset:128
	s_waitcnt vmcnt(27) lgkmcnt(0)
	v_mfma_f32_16x16x32_bf16 v[4:7], v[46:49], v[30:33], v[4:7]
	s_waitcnt vmcnt(25)
	v_mfma_f32_16x16x32_bf16 v[0:3], v[54:57], v[30:33], v[0:3]
	ds_read_b128 v[30:33], v15 offset:192
	s_waitcnt lgkmcnt(0)
	v_mfma_f32_16x16x32_bf16 v[4:7], v[50:53], v[30:33], v[4:7]
	s_waitcnt vmcnt(19)
	v_mfma_f32_16x16x32_bf16 v[0:3], v[78:81], v[30:33], v[0:3]
	ds_read_b128 v[30:33], v15 offset:256
	s_waitcnt lgkmcnt(0)
	v_mfma_f32_16x16x32_bf16 v[4:7], v[58:61], v[30:33], v[4:7]
	v_mfma_f32_16x16x32_bf16 v[0:3], v[62:65], v[30:33], v[0:3]
	ds_read_b128 v[30:33], v15 offset:320
	s_waitcnt lgkmcnt(0)
	v_mfma_f32_16x16x32_bf16 v[4:7], v[70:73], v[30:33], v[4:7]
	v_mfma_f32_16x16x32_bf16 v[0:3], v[66:69], v[30:33], v[0:3]
	ds_read_b128 v[30:33], v15 offset:384
	s_waitcnt lgkmcnt(0)
	v_mfma_f32_16x16x32_bf16 v[4:7], v[74:77], v[30:33], v[4:7]
	s_waitcnt vmcnt(17)
	v_mfma_f32_16x16x32_bf16 v[0:3], v[86:89], v[30:33], v[0:3]
	ds_read_b128 v[30:33], v15 offset:448
	s_waitcnt lgkmcnt(0)
	v_mfma_f32_16x16x32_bf16 v[4:7], v[82:85], v[30:33], v[4:7]
	s_waitcnt vmcnt(16)
	v_mfma_f32_16x16x32_bf16 v[0:3], v[90:93], v[30:33], v[0:3]
	v_add_u32_e32 v15, 0x200, v15
	v_add_co_u32_e32 v50, vcc, 0xffff7000, v16
	s_movk_i32 s10, 0xf000
	s_nop 0
	v_addc_co_u32_e32 v51, vcc, -1, v17, vcc
	v_add_co_u32_e32 v54, vcc, s10, v16
	s_nop 1
	v_addc_co_u32_e32 v55, vcc, -1, v17, vcc
	v_add_co_u32_e32 v82, vcc, s77, v16
	global_load_dwordx4 v[30:33], v[50:51], off offset:-3072
	global_load_dwordx4 v[34:37], v[50:51], off offset:-2048
	global_load_dwordx4 v[38:41], v[54:55], off offset:-3072
	global_load_dwordx4 v[42:45], v[54:55], off offset:-2048
	global_load_dwordx4 v[46:49], v[50:51], off offset:-1024
	s_nop 0
	global_load_dwordx4 v[50:53], v[50:51], off
	v_addc_co_u32_e32 v83, vcc, -1, v17, vcc
	global_load_dwordx4 v[54:57], v[54:55], off offset:-1024
	s_nop 0
	global_load_dwordx4 v[58:61], v[82:83], off offset:-3072
	global_load_dwordx4 v[62:65], v[16:17], off offset:-3072
	global_load_dwordx4 v[66:69], v[16:17], off offset:-2048
	global_load_dwordx4 v[70:73], v[82:83], off offset:-2048
	global_load_dwordx4 v[74:77], v[82:83], off offset:-1024
	global_load_dwordx4 v[78:81], v[16:17], off offset:-4096
	s_nop 0
	global_load_dwordx4 v[82:85], v[82:83], off
	s_nop 0
	global_load_dwordx4 v[86:89], v[16:17], off offset:-1024
	global_load_dwordx4 v[90:93], v[16:17], off
	v_lshl_add_u64 v[16:17], v[16:17], 0, s[12:13]
	ds_read_b128 v[94:97], v15
	s_waitcnt vmcnt(31) lgkmcnt(0)
	v_mfma_f32_16x16x32_bf16 v[4:7], v[100:103], v[94:97], v[4:7]
	ds_read_b128 v[100:103], v15 offset:64
	s_waitcnt vmcnt(29)
	v_mfma_f32_16x16x32_bf16 v[0:3], v[108:111], v[94:97], v[0:3]
	s_waitcnt lgkmcnt(0)
	v_mfma_f32_16x16x32_bf16 v[4:7], v[104:107], v[100:103], v[4:7]
	s_waitcnt vmcnt(28)
	v_mfma_f32_16x16x32_bf16 v[0:3], v[112:115], v[100:103], v[0:3]
	ds_read_b128 v[100:103], v15 offset:128
	s_waitcnt vmcnt(27) lgkmcnt(0)
	v_mfma_f32_16x16x32_bf16 v[4:7], v[116:119], v[100:103], v[4:7]
	s_waitcnt vmcnt(25)
	v_mfma_f32_16x16x32_bf16 v[0:3], v[124:127], v[100:103], v[0:3]
	ds_read_b128 v[100:103], v15 offset:192
	s_waitcnt lgkmcnt(0)
	v_mfma_f32_16x16x32_bf16 v[4:7], v[120:123], v[100:103], v[4:7]
	s_waitcnt vmcnt(19)
	v_mfma_f32_16x16x32_bf16 v[0:3], v[148:151], v[100:103], v[0:3]
	ds_read_b128 v[100:103], v15 offset:256
	s_waitcnt lgkmcnt(0)
	v_mfma_f32_16x16x32_bf16 v[4:7], v[128:131], v[100:103], v[4:7]
	v_mfma_f32_16x16x32_bf16 v[0:3], v[132:135], v[100:103], v[0:3]
	ds_read_b128 v[100:103], v15 offset:320
	s_waitcnt lgkmcnt(0)
	v_mfma_f32_16x16x32_bf16 v[4:7], v[140:143], v[100:103], v[4:7]
	v_mfma_f32_16x16x32_bf16 v[0:3], v[136:139], v[100:103], v[0:3]
	ds_read_b128 v[100:103], v15 offset:384
	s_waitcnt lgkmcnt(0)
	v_mfma_f32_16x16x32_bf16 v[4:7], v[144:147], v[100:103], v[4:7]
	s_waitcnt vmcnt(17)
	v_mfma_f32_16x16x32_bf16 v[0:3], v[156:159], v[100:103], v[0:3]
	ds_read_b128 v[100:103], v15 offset:448
	s_waitcnt lgkmcnt(0)
	v_mfma_f32_16x16x32_bf16 v[4:7], v[152:155], v[100:103], v[4:7]
	s_waitcnt vmcnt(16)
	v_mfma_f32_16x16x32_bf16 v[0:3], v[172:175], v[100:103], v[0:3]
	v_add_u32_e32 v15, 0x200, v15
	v_add_co_u32_e32 v120, vcc, 0xffff7000, v16
	s_movk_i32 s10, 0xf000
	s_nop 0
	v_addc_co_u32_e32 v121, vcc, -1, v17, vcc
	v_add_co_u32_e32 v124, vcc, s10, v16
	s_nop 1
	v_addc_co_u32_e32 v125, vcc, -1, v17, vcc
	v_add_co_u32_e32 v152, vcc, s77, v16
	global_load_dwordx4 v[100:103], v[120:121], off offset:-3072
	global_load_dwordx4 v[104:107], v[120:121], off offset:-2048
	global_load_dwordx4 v[108:111], v[124:125], off offset:-3072
	global_load_dwordx4 v[112:115], v[124:125], off offset:-2048
	global_load_dwordx4 v[116:119], v[120:121], off offset:-1024
	s_nop 0
	global_load_dwordx4 v[120:123], v[120:121], off
	v_addc_co_u32_e32 v153, vcc, -1, v17, vcc
	global_load_dwordx4 v[124:127], v[124:125], off offset:-1024
	s_nop 0
	global_load_dwordx4 v[128:131], v[152:153], off offset:-3072
	global_load_dwordx4 v[132:135], v[16:17], off offset:-3072
	global_load_dwordx4 v[136:139], v[16:17], off offset:-2048
	global_load_dwordx4 v[140:143], v[152:153], off offset:-2048
	global_load_dwordx4 v[144:147], v[152:153], off offset:-1024
	global_load_dwordx4 v[148:151], v[16:17], off offset:-4096
	s_nop 0
	global_load_dwordx4 v[152:155], v[152:153], off
	s_nop 0
	global_load_dwordx4 v[156:159], v[16:17], off offset:-1024
	global_load_dwordx4 v[172:175], v[16:17], off
	ds_read_b128 v[94:97], v15
	s_waitcnt vmcnt(31) lgkmcnt(0)
	v_mfma_f32_16x16x32_bf16 v[4:7], v[30:33], v[94:97], v[4:7]
	ds_read_b128 v[30:33], v15 offset:64
	s_waitcnt vmcnt(29)
	v_mfma_f32_16x16x32_bf16 v[0:3], v[38:41], v[94:97], v[0:3]
	s_waitcnt lgkmcnt(0)
	v_mfma_f32_16x16x32_bf16 v[4:7], v[34:37], v[30:33], v[4:7]
	s_waitcnt vmcnt(28)
	v_mfma_f32_16x16x32_bf16 v[0:3], v[42:45], v[30:33], v[0:3]
	ds_read_b128 v[30:33], v15 offset:128
	s_waitcnt vmcnt(27) lgkmcnt(0)
	v_mfma_f32_16x16x32_bf16 v[4:7], v[46:49], v[30:33], v[4:7]
	s_waitcnt vmcnt(25)
	v_mfma_f32_16x16x32_bf16 v[0:3], v[54:57], v[30:33], v[0:3]
	ds_read_b128 v[30:33], v15 offset:192
	s_waitcnt lgkmcnt(0)
	v_mfma_f32_16x16x32_bf16 v[4:7], v[50:53], v[30:33], v[4:7]
	s_waitcnt vmcnt(19)
	v_mfma_f32_16x16x32_bf16 v[0:3], v[78:81], v[30:33], v[0:3]
	ds_read_b128 v[30:33], v15 offset:256
	s_waitcnt lgkmcnt(0)
	v_mfma_f32_16x16x32_bf16 v[4:7], v[58:61], v[30:33], v[4:7]
	v_mfma_f32_16x16x32_bf16 v[0:3], v[62:65], v[30:33], v[0:3]
	ds_read_b128 v[30:33], v15 offset:320
	s_waitcnt lgkmcnt(0)
	v_mfma_f32_16x16x32_bf16 v[4:7], v[70:73], v[30:33], v[4:7]
	v_mfma_f32_16x16x32_bf16 v[0:3], v[66:69], v[30:33], v[0:3]
	ds_read_b128 v[30:33], v15 offset:384
	s_waitcnt lgkmcnt(0)
	v_mfma_f32_16x16x32_bf16 v[4:7], v[74:77], v[30:33], v[4:7]
	s_waitcnt vmcnt(17)
	v_mfma_f32_16x16x32_bf16 v[0:3], v[86:89], v[30:33], v[0:3]
	ds_read_b128 v[30:33], v15 offset:448
	s_waitcnt lgkmcnt(0)
	v_mfma_f32_16x16x32_bf16 v[4:7], v[82:85], v[30:33], v[4:7]
	s_waitcnt vmcnt(16)
	v_mfma_f32_16x16x32_bf16 v[0:3], v[90:93], v[30:33], v[0:3]
	v_add_u32_e32 v15, 0x200, v15
	ds_read_b128 v[94:97], v15
	s_waitcnt vmcnt(15) lgkmcnt(0)
	v_mfma_f32_16x16x32_bf16 v[4:7], v[100:103], v[94:97], v[4:7]
	ds_read_b128 v[100:103], v15 offset:64
	s_waitcnt vmcnt(13)
	v_mfma_f32_16x16x32_bf16 v[0:3], v[108:111], v[94:97], v[0:3]
	s_waitcnt lgkmcnt(0)
	v_mfma_f32_16x16x32_bf16 v[4:7], v[104:107], v[100:103], v[4:7]
	s_waitcnt vmcnt(12)
	v_mfma_f32_16x16x32_bf16 v[0:3], v[112:115], v[100:103], v[0:3]
	ds_read_b128 v[100:103], v15 offset:128
	s_waitcnt vmcnt(11) lgkmcnt(0)
	v_mfma_f32_16x16x32_bf16 v[4:7], v[116:119], v[100:103], v[4:7]
	s_waitcnt vmcnt(9)
	v_mfma_f32_16x16x32_bf16 v[0:3], v[124:127], v[100:103], v[0:3]
	ds_read_b128 v[100:103], v15 offset:192
	s_waitcnt lgkmcnt(0)
	v_mfma_f32_16x16x32_bf16 v[4:7], v[120:123], v[100:103], v[4:7]
	s_waitcnt vmcnt(3)
	v_mfma_f32_16x16x32_bf16 v[0:3], v[148:151], v[100:103], v[0:3]
	ds_read_b128 v[100:103], v15 offset:256
	s_waitcnt lgkmcnt(0)
	v_mfma_f32_16x16x32_bf16 v[4:7], v[128:131], v[100:103], v[4:7]
	v_mfma_f32_16x16x32_bf16 v[0:3], v[132:135], v[100:103], v[0:3]
	ds_read_b128 v[100:103], v15 offset:320
	s_waitcnt lgkmcnt(0)
	v_mfma_f32_16x16x32_bf16 v[4:7], v[140:143], v[100:103], v[4:7]
	v_mfma_f32_16x16x32_bf16 v[0:3], v[136:139], v[100:103], v[0:3]
	ds_read_b128 v[100:103], v15 offset:384
	s_waitcnt lgkmcnt(0)
	v_mfma_f32_16x16x32_bf16 v[4:7], v[144:147], v[100:103], v[4:7]
	s_waitcnt vmcnt(1)
	v_mfma_f32_16x16x32_bf16 v[0:3], v[156:159], v[100:103], v[0:3]
	ds_read_b128 v[100:103], v15 offset:448
	s_waitcnt lgkmcnt(0)
	v_mfma_f32_16x16x32_bf16 v[4:7], v[152:155], v[100:103], v[4:7]
	s_waitcnt vmcnt(0)
	v_mfma_f32_16x16x32_bf16 v[0:3], v[172:175], v[100:103], v[0:3]
	v_or_b32_e32 v16, s9, v18
	v_ashrrev_i32_e32 v17, 31, v16
	v_mov_b32_e32 v15, 0x110
	v_mad_i64_i32 v[16:17], s[6:7], s6, v15, v[16:17]
	v_lshlrev_b64 v[16:17], 10, v[16:17]
	v_lshl_add_u64 v[16:17], s[4:5], 0, v[16:17]
	v_lshl_add_u64 v[30:31], v[8:9], 2, v[16:17]
	v_mov_b32_e32 v15, v161
	v_lshl_add_u64 v[30:31], v[30:31], 0, v[14:15]
	global_store_dwordx4 v[30:31], v[4:7], off
	s_nop 1
	v_lshl_add_u64 v[4:5], v[10:11], 2, v[16:17]
	v_lshl_add_u64 v[4:5], v[4:5], 0, v[14:15]
	global_store_dwordx4 v[4:5], v[0:3], off
	s_load_dwordx2 s[6:7], s[0:1], 0x118
	s_waitcnt lgkmcnt(0)
	s_add_i32 s8, s6, s8
	s_cmpk_gt_i32 s8, 0x43f
	s_cbranch_scc0 .LBB0_430

.LBB0_651:
	s_mov_b32 s7, 0xffff2000
	v_add_co_u32_e32 v80, vcc, s7, v32
	s_mov_b32 s7, 0xffff4000
	s_nop 0
	v_addc_co_u32_e32 v81, vcc, -1, v33, vcc
	v_add_co_u32_e32 v88, vcc, s7, v32
	s_mov_b32 s7, 0xffff6000
	s_nop 0
	v_addc_co_u32_e32 v89, vcc, -1, v33, vcc
	v_add_co_u32_e32 v96, vcc, s7, v32
	s_movk_i32 s7, 0xa000
	s_nop 0
	v_addc_co_u32_e32 v97, vcc, -1, v33, vcc
	v_add_co_u32_e32 v104, vcc, s77, v32
	s_nop 1
	v_addc_co_u32_e32 v105, vcc, -1, v33, vcc
	v_add_co_u32_e32 v112, vcc, s7, v32
	s_movk_i32 s7, 0xc000
	s_nop 0
	v_addc_co_u32_e32 v113, vcc, -1, v33, vcc
	v_add_co_u32_e32 v120, vcc, s7, v32
	s_movk_i32 s7, 0xe000
	s_nop 0
	v_addc_co_u32_e32 v121, vcc, -1, v33, vcc
	v_add_co_u32_e32 v128, vcc, s7, v32
	s_nop 1
	v_addc_co_u32_e32 v129, vcc, -1, v33, vcc
	global_load_dwordx4 v[76:79], v[80:81], off offset:-1024
	s_nop 0
	global_load_dwordx4 v[80:83], v[80:81], off
	s_nop 0
	global_load_dwordx4 v[84:87], v[88:89], off offset:-1024
	s_nop 0
	global_load_dwordx4 v[88:91], v[88:89], off
	s_nop 0
	global_load_dwordx4 v[92:95], v[96:97], off offset:-1024
	s_nop 0
	global_load_dwordx4 v[96:99], v[96:97], off
	s_nop 0
	global_load_dwordx4 v[100:103], v[104:105], off offset:-1024
	s_nop 0
	global_load_dwordx4 v[104:107], v[104:105], off
	s_nop 0
	global_load_dwordx4 v[108:111], v[112:113], off offset:-1024
	s_nop 0
	global_load_dwordx4 v[112:115], v[112:113], off
	s_nop 0
	global_load_dwordx4 v[116:119], v[120:121], off offset:-1024
	s_nop 0
	global_load_dwordx4 v[120:123], v[120:121], off
	s_nop 0
	global_load_dwordx4 v[124:127], v[128:129], off offset:-1024
	s_nop 0
	global_load_dwordx4 v[128:131], v[128:129], off
	s_nop 0
	global_load_dwordx4 v[132:135], v[32:33], off offset:-1024
	global_load_dwordx4 v[136:139], v[32:33], off
	s_mov_b64 s[12:13], 0x800
	v_lshl_add_u64 v[32:33], v[32:33], 0, s[12:13]
	s_mov_b32 s7, 0xffff2000
	v_add_co_u32_e32 v148, vcc, s7, v32
	s_mov_b32 s7, 0xffff4000
	s_nop 0
	v_addc_co_u32_e32 v149, vcc, -1, v33, vcc
	v_add_co_u32_e32 v156, vcc, s7, v32
	s_mov_b32 s7, 0xffff6000
	s_nop 0
	v_addc_co_u32_e32 v157, vcc, -1, v33, vcc
	v_add_co_u32_e32 v176, vcc, s7, v32
	s_movk_i32 s7, 0xa000
	s_nop 0
	v_addc_co_u32_e32 v177, vcc, -1, v33, vcc
	v_add_co_u32_e32 v184, vcc, s77, v32
	s_nop 1
	v_addc_co_u32_e32 v185, vcc, -1, v33, vcc
	v_add_co_u32_e32 v200, vcc, s7, v32
	s_movk_i32 s7, 0xc000
	s_nop 0
	v_addc_co_u32_e32 v201, vcc, -1, v33, vcc
	v_add_co_u32_e32 v208, vcc, s7, v32
	s_movk_i32 s7, 0xe000
	s_nop 0
	v_addc_co_u32_e32 v209, vcc, -1, v33, vcc
	v_add_co_u32_e32 v240, vcc, s7, v32
	s_nop 1
	v_addc_co_u32_e32 v241, vcc, -1, v33, vcc
	global_load_dwordx4 v[144:147], v[148:149], off offset:-1024
	s_nop 0
	global_load_dwordx4 v[148:151], v[148:149], off
	s_nop 0
	global_load_dwordx4 v[152:155], v[156:157], off offset:-1024
	s_nop 0
	global_load_dwordx4 v[156:159], v[156:157], off
	s_nop 0
	global_load_dwordx4 v[172:175], v[176:177], off offset:-1024
	s_nop 0
	global_load_dwordx4 v[176:179], v[176:177], off
	s_nop 0
	global_load_dwordx4 v[180:183], v[184:185], off offset:-1024
	s_nop 0
	global_load_dwordx4 v[184:187], v[184:185], off
	s_nop 0
	global_load_dwordx4 v[196:199], v[200:201], off offset:-1024
	s_nop 0
	global_load_dwordx4 v[200:203], v[200:201], off
	s_nop 0
	global_load_dwordx4 v[204:207], v[208:209], off offset:-1024
	s_nop 0
	global_load_dwordx4 v[208:211], v[208:209], off
	s_nop 0
	global_load_dwordx4 v[236:239], v[240:241], off offset:-1024
	s_nop 0
	global_load_dwordx4 v[240:243], v[240:241], off
	s_nop 0
	global_load_dwordx4 v[244:247], v[32:33], off offset:-1024
	global_load_dwordx4 v[248:251], v[32:33], off
	s_mov_b64 s[12:13], 0x800
	v_lshl_add_u64 v[32:33], v[32:33], 0, s[12:13]
	ds_read_b128 v[140:143], v34
	s_waitcnt vmcnt(31) lgkmcnt(0)
	v_mfma_f32_16x16x32_bf16 v[28:31], v[76:79], v[140:143], v[28:31]
	ds_read_b128 v[76:79], v34 offset:64
	s_waitcnt vmcnt(29)
	v_mfma_f32_16x16x32_bf16 v[24:27], v[84:87], v[140:143], v[24:27]
	s_waitcnt vmcnt(27)
	v_mfma_f32_16x16x32_bf16 v[20:23], v[92:95], v[140:143], v[20:23]
	s_waitcnt vmcnt(25)
	v_mfma_f32_16x16x32_bf16 v[16:19], v[100:103], v[140:143], v[16:19]
	s_waitcnt vmcnt(23)
	v_mfma_f32_16x16x32_bf16 v[12:15], v[108:111], v[140:143], v[12:15]
	s_waitcnt vmcnt(21)
	v_mfma_f32_16x16x32_bf16 v[8:11], v[116:119], v[140:143], v[8:11]
	s_waitcnt vmcnt(19)
	v_mfma_f32_16x16x32_bf16 v[4:7], v[124:127], v[140:143], v[4:7]
	s_waitcnt vmcnt(17)
	v_mfma_f32_16x16x32_bf16 v[0:3], v[132:135], v[140:143], v[0:3]
	s_waitcnt lgkmcnt(0)
	v_mfma_f32_16x16x32_bf16 v[28:31], v[80:83], v[76:79], v[28:31]
	v_mfma_f32_16x16x32_bf16 v[24:27], v[88:91], v[76:79], v[24:27]
	v_mfma_f32_16x16x32_bf16 v[20:23], v[96:99], v[76:79], v[20:23]
	v_mfma_f32_16x16x32_bf16 v[16:19], v[104:107], v[76:79], v[16:19]
	v_mfma_f32_16x16x32_bf16 v[12:15], v[112:115], v[76:79], v[12:15]
	v_mfma_f32_16x16x32_bf16 v[8:11], v[120:123], v[76:79], v[8:11]
	v_mfma_f32_16x16x32_bf16 v[4:7], v[128:131], v[76:79], v[4:7]
	s_waitcnt vmcnt(16)
	v_mfma_f32_16x16x32_bf16 v[0:3], v[136:139], v[76:79], v[0:3]
	v_add_u32_e32 v34, 0x80, v34
	s_mov_b32 s7, 0xffff2000
	v_add_co_u32_e32 v80, vcc, s7, v32
	s_mov_b32 s7, 0xffff4000
	s_nop 0
	v_addc_co_u32_e32 v81, vcc, -1, v33, vcc
	v_add_co_u32_e32 v88, vcc, s7, v32
	s_mov_b32 s7, 0xffff6000
	s_nop 0
	v_addc_co_u32_e32 v89, vcc, -1, v33, vcc
	v_add_co_u32_e32 v96, vcc, s7, v32
	s_movk_i32 s7, 0xa000
	s_nop 0
	v_addc_co_u32_e32 v97, vcc, -1, v33, vcc
	v_add_co_u32_e32 v104, vcc, s77, v32
	s_nop 1
	v_addc_co_u32_e32 v105, vcc, -1, v33, vcc
	v_add_co_u32_e32 v112, vcc, s7, v32
	s_movk_i32 s7, 0xc000
	s_nop 0
	v_addc_co_u32_e32 v113, vcc, -1, v33, vcc
	v_add_co_u32_e32 v120, vcc, s7, v32
	s_movk_i32 s7, 0xe000
	s_nop 0
	v_addc_co_u32_e32 v121, vcc, -1, v33, vcc
	v_add_co_u32_e32 v128, vcc, s7, v32
	s_nop 1
	v_addc_co_u32_e32 v129, vcc, -1, v33, vcc
	global_load_dwordx4 v[76:79], v[80:81], off offset:-1024
	s_nop 0
	global_load_dwordx4 v[80:83], v[80:81], off
	s_nop 0
	global_load_dwordx4 v[84:87], v[88:89], off offset:-1024
	s_nop 0
	global_load_dwordx4 v[88:91], v[88:89], off
	s_nop 0
	global_load_dwordx4 v[92:95], v[96:97], off offset:-1024
	s_nop 0
	global_load_dwordx4 v[96:99], v[96:97], off
	s_nop 0
	global_load_dwordx4 v[100:103], v[104:105], off offset:-1024
	s_nop 0
	global_load_dwordx4 v[104:107], v[104:105], off
	s_nop 0
	global_load_dwordx4 v[108:111], v[112:113], off offset:-1024
	s_nop 0
	global_load_dwordx4 v[112:115], v[112:113], off
	s_nop 0
	global_load_dwordx4 v[116:119], v[120:121], off offset:-1024
	s_nop 0
	global_load_dwordx4 v[120:123], v[120:121], off
	s_nop 0
	global_load_dwordx4 v[124:127], v[128:129], off offset:-1024
	s_nop 0
	global_load_dwordx4 v[128:131], v[128:129], off
	s_nop 0
	global_load_dwordx4 v[132:135], v[32:33], off offset:-1024
	global_load_dwordx4 v[136:139], v[32:33], off
	s_mov_b64 s[12:13], 0x800
	v_lshl_add_u64 v[32:33], v[32:33], 0, s[12:13]
	ds_read_b128 v[140:143], v34
	s_waitcnt vmcnt(31) lgkmcnt(0)
	v_mfma_f32_16x16x32_bf16 v[28:31], v[144:147], v[140:143], v[28:31]
	ds_read_b128 v[144:147], v34 offset:64
	s_waitcnt vmcnt(29)
	v_mfma_f32_16x16x32_bf16 v[24:27], v[152:155], v[140:143], v[24:27]
	s_waitcnt vmcnt(27)
	v_mfma_f32_16x16x32_bf16 v[20:23], v[172:175], v[140:143], v[20:23]
	s_waitcnt vmcnt(25)
	v_mfma_f32_16x16x32_bf16 v[16:19], v[180:183], v[140:143], v[16:19]
	s_waitcnt vmcnt(23)
	v_mfma_f32_16x16x32_bf16 v[12:15], v[196:199], v[140:143], v[12:15]
	s_waitcnt vmcnt(21)
	v_mfma_f32_16x16x32_bf16 v[8:11], v[204:207], v[140:143], v[8:11]
	s_waitcnt vmcnt(19)
	v_mfma_f32_16x16x32_bf16 v[4:7], v[236:239], v[140:143], v[4:7]
	s_waitcnt vmcnt(17)
	v_mfma_f32_16x16x32_bf16 v[0:3], v[244:247], v[140:143], v[0:3]
	s_waitcnt lgkmcnt(0)
	v_mfma_f32_16x16x32_bf16 v[28:31], v[148:151], v[144:147], v[28:31]
	v_mfma_f32_16x16x32_bf16 v[24:27], v[156:159], v[144:147], v[24:27]
	v_mfma_f32_16x16x32_bf16 v[20:23], v[176:179], v[144:147], v[20:23]
	v_mfma_f32_16x16x32_bf16 v[16:19], v[184:187], v[144:147], v[16:19]
	v_mfma_f32_16x16x32_bf16 v[12:15], v[200:203], v[144:147], v[12:15]
	v_mfma_f32_16x16x32_bf16 v[8:11], v[208:211], v[144:147], v[8:11]
	v_mfma_f32_16x16x32_bf16 v[4:7], v[240:243], v[144:147], v[4:7]
	s_waitcnt vmcnt(16)
	v_mfma_f32_16x16x32_bf16 v[0:3], v[248:251], v[144:147], v[0:3]
	v_add_u32_e32 v34, 0x80, v34
	s_mov_b32 s7, 0xffff2000
	v_add_co_u32_e32 v148, vcc, s7, v32
	s_mov_b32 s7, 0xffff4000
	s_nop 0
	v_addc_co_u32_e32 v149, vcc, -1, v33, vcc
	v_add_co_u32_e32 v156, vcc, s7, v32
	s_mov_b32 s7, 0xffff6000
	s_nop 0
	v_addc_co_u32_e32 v157, vcc, -1, v33, vcc
	v_add_co_u32_e32 v176, vcc, s7, v32
	s_movk_i32 s7, 0xa000
	s_nop 0
	v_addc_co_u32_e32 v177, vcc, -1, v33, vcc
	v_add_co_u32_e32 v184, vcc, s77, v32
	s_nop 1
	v_addc_co_u32_e32 v185, vcc, -1, v33, vcc
	v_add_co_u32_e32 v200, vcc, s7, v32
	s_movk_i32 s7, 0xc000
	s_nop 0
	v_addc_co_u32_e32 v201, vcc, -1, v33, vcc
	v_add_co_u32_e32 v208, vcc, s7, v32
	s_movk_i32 s7, 0xe000
	s_nop 0
	v_addc_co_u32_e32 v209, vcc, -1, v33, vcc
	v_add_co_u32_e32 v240, vcc, s7, v32
	s_nop 1
	v_addc_co_u32_e32 v241, vcc, -1, v33, vcc
	global_load_dwordx4 v[144:147], v[148:149], off offset:-1024
	s_nop 0
	global_load_dwordx4 v[148:151], v[148:149], off
	s_nop 0
	global_load_dwordx4 v[152:155], v[156:157], off offset:-1024
	s_nop 0
	global_load_dwordx4 v[156:159], v[156:157], off
	s_nop 0
	global_load_dwordx4 v[172:175], v[176:177], off offset:-1024
	s_nop 0
	global_load_dwordx4 v[176:179], v[176:177], off
	s_nop 0
	global_load_dwordx4 v[180:183], v[184:185], off offset:-1024
	s_nop 0
	global_load_dwordx4 v[184:187], v[184:185], off
	s_nop 0
	global_load_dwordx4 v[196:199], v[200:201], off offset:-1024
	s_nop 0
	global_load_dwordx4 v[200:203], v[200:201], off
	s_nop 0
	global_load_dwordx4 v[204:207], v[208:209], off offset:-1024
	s_nop 0
	global_load_dwordx4 v[208:211], v[208:209], off
	s_nop 0
	global_load_dwordx4 v[236:239], v[240:241], off offset:-1024
	s_nop 0
	global_load_dwordx4 v[240:243], v[240:241], off
	s_nop 0
	global_load_dwordx4 v[244:247], v[32:33], off offset:-1024
	global_load_dwordx4 v[248:251], v[32:33], off
	ds_read_b128 v[140:143], v34
	s_waitcnt vmcnt(31) lgkmcnt(0)
	v_mfma_f32_16x16x32_bf16 v[28:31], v[76:79], v[140:143], v[28:31]
	ds_read_b128 v[76:79], v34 offset:64
	s_waitcnt vmcnt(29)
	v_mfma_f32_16x16x32_bf16 v[24:27], v[84:87], v[140:143], v[24:27]
	s_waitcnt vmcnt(27)
	v_mfma_f32_16x16x32_bf16 v[20:23], v[92:95], v[140:143], v[20:23]
	s_waitcnt vmcnt(25)
	v_mfma_f32_16x16x32_bf16 v[16:19], v[100:103], v[140:143], v[16:19]
	s_waitcnt vmcnt(23)
	v_mfma_f32_16x16x32_bf16 v[12:15], v[108:111], v[140:143], v[12:15]
	s_waitcnt vmcnt(21)
	v_mfma_f32_16x16x32_bf16 v[8:11], v[116:119], v[140:143], v[8:11]
	s_waitcnt vmcnt(19)
	v_mfma_f32_16x16x32_bf16 v[4:7], v[124:127], v[140:143], v[4:7]
	s_waitcnt vmcnt(17)
	v_mfma_f32_16x16x32_bf16 v[0:3], v[132:135], v[140:143], v[0:3]
	s_waitcnt lgkmcnt(0)
	v_mfma_f32_16x16x32_bf16 v[28:31], v[80:83], v[76:79], v[28:31]
	v_mfma_f32_16x16x32_bf16 v[24:27], v[88:91], v[76:79], v[24:27]
	v_mfma_f32_16x16x32_bf16 v[20:23], v[96:99], v[76:79], v[20:23]
	v_mfma_f32_16x16x32_bf16 v[16:19], v[104:107], v[76:79], v[16:19]
	v_mfma_f32_16x16x32_bf16 v[12:15], v[112:115], v[76:79], v[12:15]
	v_mfma_f32_16x16x32_bf16 v[8:11], v[120:123], v[76:79], v[8:11]
	v_mfma_f32_16x16x32_bf16 v[4:7], v[128:131], v[76:79], v[4:7]
	s_waitcnt vmcnt(16)
	v_mfma_f32_16x16x32_bf16 v[0:3], v[136:139], v[76:79], v[0:3]
	v_add_u32_e32 v34, 0x80, v34
	ds_read_b128 v[140:143], v34
	s_waitcnt vmcnt(15) lgkmcnt(0)
	v_mfma_f32_16x16x32_bf16 v[28:31], v[144:147], v[140:143], v[28:31]
	ds_read_b128 v[144:147], v34 offset:64
	s_waitcnt vmcnt(13)
	v_mfma_f32_16x16x32_bf16 v[24:27], v[152:155], v[140:143], v[24:27]
	s_waitcnt vmcnt(11)
	v_mfma_f32_16x16x32_bf16 v[20:23], v[172:175], v[140:143], v[20:23]
	s_waitcnt vmcnt(9)
	v_mfma_f32_16x16x32_bf16 v[16:19], v[180:183], v[140:143], v[16:19]
	s_waitcnt vmcnt(7)
	v_mfma_f32_16x16x32_bf16 v[12:15], v[196:199], v[140:143], v[12:15]
	s_waitcnt vmcnt(5)
	v_mfma_f32_16x16x32_bf16 v[8:11], v[204:207], v[140:143], v[8:11]
	s_waitcnt vmcnt(3)
	v_mfma_f32_16x16x32_bf16 v[4:7], v[236:239], v[140:143], v[4:7]
	s_waitcnt vmcnt(1)
	v_mfma_f32_16x16x32_bf16 v[0:3], v[244:247], v[140:143], v[0:3]
	s_waitcnt lgkmcnt(0)
	v_mfma_f32_16x16x32_bf16 v[28:31], v[148:151], v[144:147], v[28:31]
	v_mfma_f32_16x16x32_bf16 v[24:27], v[156:159], v[144:147], v[24:27]
	v_mfma_f32_16x16x32_bf16 v[20:23], v[176:179], v[144:147], v[20:23]
	v_mfma_f32_16x16x32_bf16 v[16:19], v[184:187], v[144:147], v[16:19]
	v_mfma_f32_16x16x32_bf16 v[12:15], v[200:203], v[144:147], v[12:15]
	v_mfma_f32_16x16x32_bf16 v[8:11], v[208:211], v[144:147], v[8:11]
	v_mfma_f32_16x16x32_bf16 v[4:7], v[240:243], v[144:147], v[4:7]
	s_waitcnt vmcnt(0)
	v_mfma_f32_16x16x32_bf16 v[0:3], v[248:251], v[144:147], v[0:3]
	v_mul_f32_e32 v32, 0x3d372713, v28
	v_mul_f32_e32 v32, v28, v32
	v_fma_f32 v32, v28, v32, v28
	v_mul_f32_e32 v32, 0x3f4c422a, v32
	s_mov_b32 s6, 0x3f200000
	v_cmp_nlt_f32_e64 s[6:7], |v32|, s6
	s_and_saveexec_b64 s[12:13], s[6:7]
	s_xor_b64 s[6:7], exec, s[12:13]
	s_cbranch_execz .LBB0_654
	v_add_f32_e64 v33, |v32|, |v32|
	v_mul_f32_e32 v34, 0x3fb8aa3b, v33
	v_rndne_f32_e32 v35, v34
	s_mov_b32 s12, 0x3fb8aa3b
	v_sub_f32_e32 v76, v34, v35
	v_fma_f32 v34, v33, s12, -v34
	v_fmac_f32_e32 v34, 0x32a5705f, v33
	v_add_f32_e32 v34, v76, v34
	v_cvt_i32_f32_e32 v35, v35
	v_exp_f32_e32 v34, v34
	s_mov_b32 s12, 0xc2ce8ed0
	v_cmp_ngt_f32_e32 vcc, s12, v33
	s_mov_b32 s12, 0x42b17218
	v_ldexp_f32 v34, v34, v35
	v_cndmask_b32_e32 v34, 0, v34, vcc
	v_cmp_nlt_f32_e32 vcc, s12, v33
	s_nop 1
	v_cndmask_b32_e32 v33, v231, v34, vcc
	v_add_f32_e32 v33, 1.0, v33
	v_rcp_f32_e32 v33, v33
	s_nop 0
	v_fma_f32 v33, v33, -2.0, 1.0
